# context-row norm at the phase end: one polling wave per workgroup, eleven slabs read in two rounds
# speedup vs baseline: 1.0054x; 1.0054x over previous
.Lcx_go:
	v_readlane_b32 s3, v254, 58
	s_sub_u32 s3, s3, 64
	s_cmp_lt_u32 s3, 32
	s_cbranch_scc0 .Lcx_skip
	v_readfirstlane_b32 s12, v202
	s_lshr_b32 s12, s12, 6
	s_lshl_b32 s84, s3, 3
	s_add_i32 s84, s84, s12
	v_and_b32_e32 v197, 63, v202
	v_lshlrev_b32_e32 v190, 4, v197
	v_lshlrev_b32_e32 v191, 3, v197
	v_mov_b32_e32 v193, 0
	s_cmp_eq_u32 s1, 5
	s_cselect_b32 s85, 0, 1
	s_movk_i32 s88, 352
	s_cselect_b32 s88, 128, s88
	s_cselect_b32 s89, 4, 11
	s_movk_i32 s3, 0x3e40
	s_cselect_b32 s3, 0x3e00, s3
	s_add_i32 s86, s2, s85
	s_add_i32 s87, s2, 1
	s_mul_i32 s88, s88, s87
	s_add_u32 s18, s8, s3
	s_addc_u32 s19, s9, 0
	v_readlane_b32 s12, v254, 21
	v_readlane_b32 s13, v254, 22
	v_readlane_b32 s14, v254, 54
	v_readlane_b32 s15, v254, 55
	s_cmp_eq_u32 s1, 5
	s_cselect_b32 s12, s12, s14
	s_cselect_b32 s13, s13, s15
	s_cselect_b32 s3, 0x3000, 0
	s_lshl_b32 s14, s86, 12
	s_add_u32 s12, s12, s14
	s_addc_u32 s13, s13, 0
	v_readlane_b32 s16, v252, 11
	v_readlane_b32 s17, v252, 12
	s_mul_i32 s14, s86, 0xc000
	s_add_i32 s14, s14, s3
	s_add_i32 s14, s14, 0x6000
	s_add_u32 s16, s16, s14
	s_addc_u32 s17, s17, 0
	s_add_u32 s14, s16, 0x1000
	s_addc_u32 s15, s17, 0
	s_nop 1
	global_load_dwordx4 v[18:21], v190, s[12:13]
	global_load_dwordx4 v[34:37], v190, s[14:15]
	global_load_dwordx4 v[50:53], v190, s[16:17]
	global_load_dwordx4 v[22:25], v190, s[12:13] offset:1024
	global_load_dwordx4 v[38:41], v190, s[14:15] offset:1024
	global_load_dwordx4 v[54:57], v190, s[16:17] offset:1024
	global_load_dwordx4 v[26:29], v190, s[12:13] offset:2048
	global_load_dwordx4 v[42:45], v190, s[14:15] offset:2048
	global_load_dwordx4 v[58:61], v190, s[16:17] offset:2048
	global_load_dwordx4 v[30:33], v190, s[12:13] offset:3072
	global_load_dwordx4 v[46:49], v190, s[14:15] offset:3072
	global_load_dwordx4 v[62:65], v190, s[16:17] offset:3072
	v_readlane_b32 s40, v252, 5
	v_readlane_b32 s41, v252, 6
	s_lshl_b32 s3, s84, 12
	s_add_u32 s40, s40, s3
	s_addc_u32 s41, s41, 0
	s_add_u32 s40, s40, 0x4000000
	s_addc_u32 s41, s41, 0
	v_readlane_b32 s42, v254, 46
	v_readlane_b32 s43, v254, 47
	s_add_u32 s42, s42, s3
	s_addc_u32 s43, s43, 0
	s_cmp_eq_u32 s86, 0
	s_cselect_b32 s42, s42, s40
	s_cselect_b32 s43, s43, s41
	s_nop 1
	global_load_dwordx4 v[2:5], v190, s[42:43]
	global_load_dwordx4 v[6:9], v190, s[42:43] offset:1024
	global_load_dwordx4 v[10:13], v190, s[42:43] offset:2048
	global_load_dwordx4 v[14:17], v190, s[42:43] offset:3072
	s_add_u32 s44, s8, 0x16acc000
	s_addc_u32 s45, s9, 0
	s_add_u32 s44, s44, s3
	s_addc_u32 s45, s45, 0
	v_readfirstlane_b32 s3, v202
	s_cmp_lt_u32 s3, 64
	s_cbranch_scc0 .Lcx_ready
	s_mov_b32 s3, 0

.Lcx_ready:
	s_barrier
	s_cmp_eq_u32 s89, 4
	s_cbranch_scc0 .Lcx_eleven
	global_load_dwordx4 v[70:73], v190, s[44:45] sc0 sc1
	global_load_dwordx4 v[74:77], v190, s[44:45] offset:1024 sc0 sc1
	global_load_dwordx4 v[78:81], v190, s[44:45] offset:2048 sc0 sc1
	global_load_dwordx4 v[82:85], v190, s[44:45] offset:3072 sc0 sc1
	s_add_u32 s44, s44, 0x100000
	s_addc_u32 s45, s45, 0
	global_load_dwordx4 v[86:89], v190, s[44:45] sc0 sc1
	global_load_dwordx4 v[90:93], v190, s[44:45] offset:1024 sc0 sc1
	global_load_dwordx4 v[94:97], v190, s[44:45] offset:2048 sc0 sc1
	global_load_dwordx4 v[98:101], v190, s[44:45] offset:3072 sc0 sc1
	s_add_u32 s44, s44, 0x100000
	s_addc_u32 s45, s45, 0
	global_load_dwordx4 v[102:105], v190, s[44:45] sc0 sc1
	global_load_dwordx4 v[106:109], v190, s[44:45] offset:1024 sc0 sc1
	global_load_dwordx4 v[110:113], v190, s[44:45] offset:2048 sc0 sc1
	global_load_dwordx4 v[114:117], v190, s[44:45] offset:3072 sc0 sc1
	s_add_u32 s44, s44, 0x100000
	s_addc_u32 s45, s45, 0
	global_load_dwordx4 v[118:121], v190, s[44:45] sc0 sc1
	global_load_dwordx4 v[122:125], v190, s[44:45] offset:1024 sc0 sc1
	global_load_dwordx4 v[126:129], v190, s[44:45] offset:2048 sc0 sc1
	global_load_dwordx4 v[130:133], v190, s[44:45] offset:3072 sc0 sc1
	s_add_u32 s44, s44, 0x100000
	s_addc_u32 s45, s45, 0
	s_waitcnt vmcnt(0)
	v_add_f32_e32 v2, v2, v70
	v_add_f32_e32 v3, v3, v71
	v_add_f32_e32 v4, v4, v72
	v_add_f32_e32 v5, v5, v73
	v_add_f32_e32 v6, v6, v74
	v_add_f32_e32 v7, v7, v75
	v_add_f32_e32 v8, v8, v76
	v_add_f32_e32 v9, v9, v77
	v_add_f32_e32 v10, v10, v78
	v_add_f32_e32 v11, v11, v79
	v_add_f32_e32 v12, v12, v80
	v_add_f32_e32 v13, v13, v81
	v_add_f32_e32 v14, v14, v82
	v_add_f32_e32 v15, v15, v83
	v_add_f32_e32 v16, v16, v84
	v_add_f32_e32 v17, v17, v85
	v_add_f32_e32 v2, v2, v86
	v_add_f32_e32 v3, v3, v87
	v_add_f32_e32 v4, v4, v88
	v_add_f32_e32 v5, v5, v89
	v_add_f32_e32 v6, v6, v90
	v_add_f32_e32 v7, v7, v91
	v_add_f32_e32 v8, v8, v92
	v_add_f32_e32 v9, v9, v93
	v_add_f32_e32 v10, v10, v94
	v_add_f32_e32 v11, v11, v95
	v_add_f32_e32 v12, v12, v96
	v_add_f32_e32 v13, v13, v97
	v_add_f32_e32 v14, v14, v98
	v_add_f32_e32 v15, v15, v99
	v_add_f32_e32 v16, v16, v100
	v_add_f32_e32 v17, v17, v101
	v_add_f32_e32 v2, v2, v102
	v_add_f32_e32 v3, v3, v103
	v_add_f32_e32 v4, v4, v104
	v_add_f32_e32 v5, v5, v105
	v_add_f32_e32 v6, v6, v106
	v_add_f32_e32 v7, v7, v107
	v_add_f32_e32 v8, v8, v108
	v_add_f32_e32 v9, v9, v109
	v_add_f32_e32 v10, v10, v110
	v_add_f32_e32 v11, v11, v111
	v_add_f32_e32 v12, v12, v112
	v_add_f32_e32 v13, v13, v113
	v_add_f32_e32 v14, v14, v114
	v_add_f32_e32 v15, v15, v115
	v_add_f32_e32 v16, v16, v116
	v_add_f32_e32 v17, v17, v117
	v_add_f32_e32 v2, v2, v118
	v_add_f32_e32 v3, v3, v119
	v_add_f32_e32 v4, v4, v120
	v_add_f32_e32 v5, v5, v121
	v_add_f32_e32 v6, v6, v122
	v_add_f32_e32 v7, v7, v123
	v_add_f32_e32 v8, v8, v124
	v_add_f32_e32 v9, v9, v125
	v_add_f32_e32 v10, v10, v126
	v_add_f32_e32 v11, v11, v127
	v_add_f32_e32 v12, v12, v128
	v_add_f32_e32 v13, v13, v129
	v_add_f32_e32 v14, v14, v130
	v_add_f32_e32 v15, v15, v131
	v_add_f32_e32 v16, v16, v132
	v_add_f32_e32 v17, v17, v133
	s_branch .Lcx_summed
.Lcx_eleven:
	global_load_dwordx4 v[70:73], v190, s[44:45] sc0 sc1
	global_load_dwordx4 v[74:77], v190, s[44:45] offset:1024 sc0 sc1
	global_load_dwordx4 v[78:81], v190, s[44:45] offset:2048 sc0 sc1
	global_load_dwordx4 v[82:85], v190, s[44:45] offset:3072 sc0 sc1
	s_add_u32 s44, s44, 0x100000
	s_addc_u32 s45, s45, 0
	global_load_dwordx4 v[86:89], v190, s[44:45] sc0 sc1
	global_load_dwordx4 v[90:93], v190, s[44:45] offset:1024 sc0 sc1
	global_load_dwordx4 v[94:97], v190, s[44:45] offset:2048 sc0 sc1
	global_load_dwordx4 v[98:101], v190, s[44:45] offset:3072 sc0 sc1
	s_add_u32 s44, s44, 0x100000
	s_addc_u32 s45, s45, 0
	global_load_dwordx4 v[102:105], v190, s[44:45] sc0 sc1
	global_load_dwordx4 v[106:109], v190, s[44:45] offset:1024 sc0 sc1
	global_load_dwordx4 v[110:113], v190, s[44:45] offset:2048 sc0 sc1
	global_load_dwordx4 v[114:117], v190, s[44:45] offset:3072 sc0 sc1
	s_add_u32 s44, s44, 0x100000
	s_addc_u32 s45, s45, 0
	global_load_dwordx4 v[118:121], v190, s[44:45] sc0 sc1
	global_load_dwordx4 v[122:125], v190, s[44:45] offset:1024 sc0 sc1
	global_load_dwordx4 v[126:129], v190, s[44:45] offset:2048 sc0 sc1
	global_load_dwordx4 v[130:133], v190, s[44:45] offset:3072 sc0 sc1
	s_add_u32 s44, s44, 0x100000
	s_addc_u32 s45, s45, 0
	global_load_dwordx4 v[134:137], v190, s[44:45] sc0 sc1
	global_load_dwordx4 v[138:141], v190, s[44:45] offset:1024 sc0 sc1
	global_load_dwordx4 v[142:145], v190, s[44:45] offset:2048 sc0 sc1
	global_load_dwordx4 v[146:149], v190, s[44:45] offset:3072 sc0 sc1
	s_add_u32 s44, s44, 0x100000
	s_addc_u32 s45, s45, 0
	global_load_dwordx4 v[150:153], v190, s[44:45] sc0 sc1
	global_load_dwordx4 v[154:157], v190, s[44:45] offset:1024 sc0 sc1
	global_load_dwordx4 v[158:161], v190, s[44:45] offset:2048 sc0 sc1
	global_load_dwordx4 v[162:165], v190, s[44:45] offset:3072 sc0 sc1
	s_add_u32 s44, s44, 0x100000
	s_addc_u32 s45, s45, 0
	s_waitcnt vmcnt(0)
	v_add_f32_e32 v2, v2, v70
	v_add_f32_e32 v3, v3, v71
	v_add_f32_e32 v4, v4, v72
	v_add_f32_e32 v5, v5, v73
	v_add_f32_e32 v6, v6, v74
	v_add_f32_e32 v7, v7, v75
	v_add_f32_e32 v8, v8, v76
	v_add_f32_e32 v9, v9, v77
	v_add_f32_e32 v10, v10, v78
	v_add_f32_e32 v11, v11, v79
	v_add_f32_e32 v12, v12, v80
	v_add_f32_e32 v13, v13, v81
	v_add_f32_e32 v14, v14, v82
	v_add_f32_e32 v15, v15, v83
	v_add_f32_e32 v16, v16, v84
	v_add_f32_e32 v17, v17, v85
	v_add_f32_e32 v2, v2, v86
	v_add_f32_e32 v3, v3, v87
	v_add_f32_e32 v4, v4, v88
	v_add_f32_e32 v5, v5, v89
	v_add_f32_e32 v6, v6, v90
	v_add_f32_e32 v7, v7, v91
	v_add_f32_e32 v8, v8, v92
	v_add_f32_e32 v9, v9, v93
	v_add_f32_e32 v10, v10, v94
	v_add_f32_e32 v11, v11, v95
	v_add_f32_e32 v12, v12, v96
	v_add_f32_e32 v13, v13, v97
	v_add_f32_e32 v14, v14, v98
	v_add_f32_e32 v15, v15, v99
	v_add_f32_e32 v16, v16, v100
	v_add_f32_e32 v17, v17, v101
	v_add_f32_e32 v2, v2, v102
	v_add_f32_e32 v3, v3, v103
	v_add_f32_e32 v4, v4, v104
	v_add_f32_e32 v5, v5, v105
	v_add_f32_e32 v6, v6, v106
	v_add_f32_e32 v7, v7, v107
	v_add_f32_e32 v8, v8, v108
	v_add_f32_e32 v9, v9, v109
	v_add_f32_e32 v10, v10, v110
	v_add_f32_e32 v11, v11, v111
	v_add_f32_e32 v12, v12, v112
	v_add_f32_e32 v13, v13, v113
	v_add_f32_e32 v14, v14, v114
	v_add_f32_e32 v15, v15, v115
	v_add_f32_e32 v16, v16, v116
	v_add_f32_e32 v17, v17, v117
	v_add_f32_e32 v2, v2, v118
	v_add_f32_e32 v3, v3, v119
	v_add_f32_e32 v4, v4, v120
	v_add_f32_e32 v5, v5, v121
	v_add_f32_e32 v6, v6, v122
	v_add_f32_e32 v7, v7, v123
	v_add_f32_e32 v8, v8, v124
	v_add_f32_e32 v9, v9, v125
	v_add_f32_e32 v10, v10, v126
	v_add_f32_e32 v11, v11, v127
	v_add_f32_e32 v12, v12, v128
	v_add_f32_e32 v13, v13, v129
	v_add_f32_e32 v14, v14, v130
	v_add_f32_e32 v15, v15, v131
	v_add_f32_e32 v16, v16, v132
	v_add_f32_e32 v17, v17, v133
	v_add_f32_e32 v2, v2, v134
	v_add_f32_e32 v3, v3, v135
	v_add_f32_e32 v4, v4, v136
	v_add_f32_e32 v5, v5, v137
	v_add_f32_e32 v6, v6, v138
	v_add_f32_e32 v7, v7, v139
	v_add_f32_e32 v8, v8, v140
	v_add_f32_e32 v9, v9, v141
	v_add_f32_e32 v10, v10, v142
	v_add_f32_e32 v11, v11, v143
	v_add_f32_e32 v12, v12, v144
	v_add_f32_e32 v13, v13, v145
	v_add_f32_e32 v14, v14, v146
	v_add_f32_e32 v15, v15, v147
	v_add_f32_e32 v16, v16, v148
	v_add_f32_e32 v17, v17, v149
	v_add_f32_e32 v2, v2, v150
	v_add_f32_e32 v3, v3, v151
	v_add_f32_e32 v4, v4, v152
	v_add_f32_e32 v5, v5, v153
	v_add_f32_e32 v6, v6, v154
	v_add_f32_e32 v7, v7, v155
	v_add_f32_e32 v8, v8, v156
	v_add_f32_e32 v9, v9, v157
	v_add_f32_e32 v10, v10, v158
	v_add_f32_e32 v11, v11, v159
	v_add_f32_e32 v12, v12, v160
	v_add_f32_e32 v13, v13, v161
	v_add_f32_e32 v14, v14, v162
	v_add_f32_e32 v15, v15, v163
	v_add_f32_e32 v16, v16, v164
	v_add_f32_e32 v17, v17, v165
	global_load_dwordx4 v[70:73], v190, s[44:45] sc0 sc1
	global_load_dwordx4 v[74:77], v190, s[44:45] offset:1024 sc0 sc1
	global_load_dwordx4 v[78:81], v190, s[44:45] offset:2048 sc0 sc1
	global_load_dwordx4 v[82:85], v190, s[44:45] offset:3072 sc0 sc1
	s_add_u32 s44, s44, 0x100000
	s_addc_u32 s45, s45, 0
	global_load_dwordx4 v[86:89], v190, s[44:45] sc0 sc1
	global_load_dwordx4 v[90:93], v190, s[44:45] offset:1024 sc0 sc1
	global_load_dwordx4 v[94:97], v190, s[44:45] offset:2048 sc0 sc1
	global_load_dwordx4 v[98:101], v190, s[44:45] offset:3072 sc0 sc1
	s_add_u32 s44, s44, 0x100000
	s_addc_u32 s45, s45, 0
	global_load_dwordx4 v[102:105], v190, s[44:45] sc0 sc1
	global_load_dwordx4 v[106:109], v190, s[44:45] offset:1024 sc0 sc1
	global_load_dwordx4 v[110:113], v190, s[44:45] offset:2048 sc0 sc1
	global_load_dwordx4 v[114:117], v190, s[44:45] offset:3072 sc0 sc1
	s_add_u32 s44, s44, 0x100000
	s_addc_u32 s45, s45, 0
	global_load_dwordx4 v[118:121], v190, s[44:45] sc0 sc1
	global_load_dwordx4 v[122:125], v190, s[44:45] offset:1024 sc0 sc1
	global_load_dwordx4 v[126:129], v190, s[44:45] offset:2048 sc0 sc1
	global_load_dwordx4 v[130:133], v190, s[44:45] offset:3072 sc0 sc1
	s_add_u32 s44, s44, 0x100000
	s_addc_u32 s45, s45, 0
	global_load_dwordx4 v[134:137], v190, s[44:45] sc0 sc1
	global_load_dwordx4 v[138:141], v190, s[44:45] offset:1024 sc0 sc1
	global_load_dwordx4 v[142:145], v190, s[44:45] offset:2048 sc0 sc1
	global_load_dwordx4 v[146:149], v190, s[44:45] offset:3072 sc0 sc1
	s_add_u32 s44, s44, 0x100000
	s_addc_u32 s45, s45, 0
	s_waitcnt vmcnt(0)
	v_add_f32_e32 v2, v2, v70
	v_add_f32_e32 v3, v3, v71
	v_add_f32_e32 v4, v4, v72
	v_add_f32_e32 v5, v5, v73
	v_add_f32_e32 v6, v6, v74
	v_add_f32_e32 v7, v7, v75
	v_add_f32_e32 v8, v8, v76
	v_add_f32_e32 v9, v9, v77
	v_add_f32_e32 v10, v10, v78
	v_add_f32_e32 v11, v11, v79
	v_add_f32_e32 v12, v12, v80
	v_add_f32_e32 v13, v13, v81
	v_add_f32_e32 v14, v14, v82
	v_add_f32_e32 v15, v15, v83
	v_add_f32_e32 v16, v16, v84
	v_add_f32_e32 v17, v17, v85
	v_add_f32_e32 v2, v2, v86
	v_add_f32_e32 v3, v3, v87
	v_add_f32_e32 v4, v4, v88
	v_add_f32_e32 v5, v5, v89
	v_add_f32_e32 v6, v6, v90
	v_add_f32_e32 v7, v7, v91
	v_add_f32_e32 v8, v8, v92
	v_add_f32_e32 v9, v9, v93
	v_add_f32_e32 v10, v10, v94
	v_add_f32_e32 v11, v11, v95
	v_add_f32_e32 v12, v12, v96
	v_add_f32_e32 v13, v13, v97
	v_add_f32_e32 v14, v14, v98
	v_add_f32_e32 v15, v15, v99
	v_add_f32_e32 v16, v16, v100
	v_add_f32_e32 v17, v17, v101
	v_add_f32_e32 v2, v2, v102
	v_add_f32_e32 v3, v3, v103
	v_add_f32_e32 v4, v4, v104
	v_add_f32_e32 v5, v5, v105
	v_add_f32_e32 v6, v6, v106
	v_add_f32_e32 v7, v7, v107
	v_add_f32_e32 v8, v8, v108
	v_add_f32_e32 v9, v9, v109
	v_add_f32_e32 v10, v10, v110
	v_add_f32_e32 v11, v11, v111
	v_add_f32_e32 v12, v12, v112
	v_add_f32_e32 v13, v13, v113
	v_add_f32_e32 v14, v14, v114
	v_add_f32_e32 v15, v15, v115
	v_add_f32_e32 v16, v16, v116
	v_add_f32_e32 v17, v17, v117
	v_add_f32_e32 v2, v2, v118
	v_add_f32_e32 v3, v3, v119
	v_add_f32_e32 v4, v4, v120
	v_add_f32_e32 v5, v5, v121
	v_add_f32_e32 v6, v6, v122
	v_add_f32_e32 v7, v7, v123
	v_add_f32_e32 v8, v8, v124
	v_add_f32_e32 v9, v9, v125
	v_add_f32_e32 v10, v10, v126
	v_add_f32_e32 v11, v11, v127
	v_add_f32_e32 v12, v12, v128
	v_add_f32_e32 v13, v13, v129
	v_add_f32_e32 v14, v14, v130
	v_add_f32_e32 v15, v15, v131
	v_add_f32_e32 v16, v16, v132
	v_add_f32_e32 v17, v17, v133
	v_add_f32_e32 v2, v2, v134
	v_add_f32_e32 v3, v3, v135
	v_add_f32_e32 v4, v4, v136
	v_add_f32_e32 v5, v5, v137
	v_add_f32_e32 v6, v6, v138
	v_add_f32_e32 v7, v7, v139
	v_add_f32_e32 v8, v8, v140
	v_add_f32_e32 v9, v9, v141
	v_add_f32_e32 v10, v10, v142
	v_add_f32_e32 v11, v11, v143
	v_add_f32_e32 v12, v12, v144
	v_add_f32_e32 v13, v13, v145
	v_add_f32_e32 v14, v14, v146
	v_add_f32_e32 v15, v15, v147
	v_add_f32_e32 v16, v16, v148
	v_add_f32_e32 v17, v17, v149
